# v16 + the four GEMM K-loop heads aligned to 64 bytes (code placement)
# baseline (speedup 1.0000x reference)
; template <class Epi, bool ALIGN_EPI = true>
; __device__ __forceinline__ void gemm_phase(LAS unsigned char* lds, const Gemm g, const Order& S, const Epi& E) {
;     ...
;         const bool has_next = S.next(ui + 1, nxt);
;         const char* nA = has_next ? (const char*)g.A + (size_t)nxt.pm * tstepA + (size_t)(nxt.k0 >> 6) * kstepA : cA; const char* nB = has_next ? (const char*)g.Bt + (size_t)nxt.pn * tstepB + (size_t)(nxt.k0 >> 6) * kstepB : cB;
;         const int nt = cur.nt;
;         for (int t = 0; t < nt; t += 2) {
;             const bool last = (t == nt - 2);
;             const char* a1 = cA + (size_t)(t + 1) * kstepA;
;             const char* a2 = last ? nA : cA + (size_t)(t + 2) * kstepA; const char* b2 = last ? nB : cB + (size_t)(t + 2) * kstepB;
;             const char* a3 = a2 + kstepA; const char* b3 = b2 + kstepB;
.LBB0_185:
	s_add_u32 s90, s58, 0x10000
	s_addc_u32 s91, s59, 0
	s_ashr_i32 s53, s52, 31
	s_lshl_b64 s[34:35], s[52:53], 19
	s_add_u32 s56, s92, s34
	s_addc_u32 s57, s93, s35
	s_and_b64 s[34:35], s[38:39], exec
	s_cselect_b32 s34, s57, s45
	s_cselect_b32 s35, s56, s44
	s_ashr_i32 s51, s50, 31
	s_lshl_b64 s[54:55], s[50:51], 19
	s_add_u32 s54, s68, s54
	s_addc_u32 s55, s69, s55
	s_and_b64 s[60:61], s[38:39], exec
	s_cselect_b32 s51, s55, s59
	s_cselect_b32 s53, s54, s58
	s_add_u32 s58, s44, 0xc000
	s_addc_u32 s59, s45, 0
	v_lshl_add_u64 v[130:131], s[58:59], 0, v[158:159]
	v_lshl_add_u64 v[132:133], s[58:59], 0, v[160:161]
	s_mov_b32 s92, -2
	s_mov_b64 s[58:59], 0
	.p2alignl 6, 3212836864

; template <class Epi, bool ALIGN_EPI = true>
; __device__ __forceinline__ void gemm_phase(LAS unsigned char* lds, const Gemm g, const Order& S, const Epi& E) {
;     ...
;         const bool has_next = S.next(ui + 1, nxt);
;         const char* nA = has_next ? (const char*)g.A + (size_t)nxt.pm * tstepA + (size_t)(nxt.k0 >> 6) * kstepA : cA; const char* nB = has_next ? (const char*)g.Bt + (size_t)nxt.pn * tstepB + (size_t)(nxt.k0 >> 6) * kstepB : cB;
;         const int nt = cur.nt;
;         for (int t = 0; t < nt; t += 2) {
;             const bool last = (t == nt - 2);
;             const char* a1 = cA + (size_t)(t + 1) * kstepA;
;             const char* a2 = last ? nA : cA + (size_t)(t + 2) * kstepA; const char* b2 = last ? nB : cB + (size_t)(t + 2) * kstepB;
;             const char* a3 = a2 + kstepA; const char* b3 = b2 + kstepB;
;     ...
; #pragma unroll
;         for (int a = 0; a < 2; ++a)
; #pragma unroll
;             for (int b = 0; b < 2; ++b)
; #pragma unroll
;                 for (int m = 0; m < 4; ++m)
; #pragma unroll
;                     for (int n = 0; n < 2; ++n) acc[a][b][m][n] = (f32x4){0.f, 0.f, 0.f, 0.f};
;         cur = nxt; cA = nA; cB = nB; ++ui;
.LBB0_241:
	s_ashr_i32 s47, s46, 31
	s_lshl_b64 s[50:51], s[46:47], 21
	v_readlane_b32 s28, v254, 59
	v_readlane_b32 s29, v254, 60
	s_add_u32 s45, s28, s50
	s_addc_u32 s47, s29, s51
	s_add_u32 s50, s45, s52
	s_addc_u32 s51, s47, s53
	s_and_b64 s[62:63], s[48:49], exec
	s_cselect_b32 s47, s51, s59
	s_cselect_b32 s55, s50, s58
	s_ashr_i32 s45, s44, 31
	s_lshl_b64 s[62:63], s[44:45], 21
	s_add_u32 s45, s69, s62
	s_addc_u32 s57, s70, s63
	s_add_u32 s52, s45, s52
	s_addc_u32 s53, s57, s53
	s_and_b64 s[62:63], s[48:49], exec
	s_cselect_b32 s45, s53, s61
	s_cselect_b32 s57, s52, s60
	s_add_i32 s88, s86, -2
	s_add_u32 s58, s58, 0xc000
	s_addc_u32 s59, s59, 0
	s_add_u32 s89, s60, 0x10000
	v_mov_b32_e32 v2, 0
	s_mov_b32 s43, s65
	s_addc_u32 s90, s61, 0
	s_mov_b32 s60, 0
	v_mov_b32_e32 v3, v2
	v_mov_b32_e32 v4, v2
	v_mov_b32_e32 v5, v2
	v_mov_b32_e32 v6, v2
	v_mov_b32_e32 v7, v2
	v_mov_b32_e32 v8, v2
	v_mov_b32_e32 v9, v2
	v_mov_b32_e32 v18, v2
	v_mov_b32_e32 v19, v2
	v_mov_b32_e32 v20, v2
	v_mov_b32_e32 v21, v2
	v_mov_b32_e32 v22, v2
	v_mov_b32_e32 v23, v2
	v_mov_b32_e32 v24, v2
	v_mov_b32_e32 v25, v2
	v_mov_b32_e32 v34, v2
	v_mov_b32_e32 v35, v2
	v_mov_b32_e32 v36, v2
	v_mov_b32_e32 v37, v2
	v_mov_b32_e32 v38, v2
	v_mov_b32_e32 v39, v2
	v_mov_b32_e32 v40, v2
	v_mov_b32_e32 v41, v2
	v_mov_b32_e32 v50, v2
	v_mov_b32_e32 v51, v2
	v_mov_b32_e32 v52, v2
	v_mov_b32_e32 v53, v2
	v_mov_b32_e32 v54, v2
	v_mov_b32_e32 v55, v2
	v_mov_b32_e32 v56, v2
	v_mov_b32_e32 v57, v2
	v_mov_b32_e32 v10, v2
	v_mov_b32_e32 v11, v2
	v_mov_b32_e32 v12, v2
	v_mov_b32_e32 v13, v2
	v_mov_b32_e32 v14, v2
	v_mov_b32_e32 v15, v2
	v_mov_b32_e32 v16, v2
	v_mov_b32_e32 v17, v2
	v_mov_b32_e32 v26, v2
	v_mov_b32_e32 v27, v2
	v_mov_b32_e32 v28, v2
	v_mov_b32_e32 v29, v2
	v_mov_b32_e32 v30, v2
	v_mov_b32_e32 v31, v2
	v_mov_b32_e32 v32, v2
	v_mov_b32_e32 v33, v2
	v_mov_b32_e32 v42, v2
	v_mov_b32_e32 v43, v2
	v_mov_b32_e32 v44, v2
	v_mov_b32_e32 v45, v2
	v_mov_b32_e32 v46, v2
	v_mov_b32_e32 v47, v2
	v_mov_b32_e32 v48, v2
	v_mov_b32_e32 v49, v2
	v_mov_b32_e32 v58, v2
	v_mov_b32_e32 v59, v2
	v_mov_b32_e32 v60, v2
	v_mov_b32_e32 v61, v2
	v_mov_b32_e32 v70, v2
	v_mov_b32_e32 v71, v2
	v_mov_b32_e32 v72, v2
	v_mov_b32_e32 v73, v2
	v_mov_b32_e32 v114, v2
	v_mov_b32_e32 v115, v2
	v_mov_b32_e32 v116, v2
	v_mov_b32_e32 v117, v2
	v_mov_b32_e32 v118, v2
	v_mov_b32_e32 v119, v2
	v_mov_b32_e32 v120, v2
	v_mov_b32_e32 v121, v2
	v_mov_b32_e32 v130, v2
	v_mov_b32_e32 v131, v2
	v_mov_b32_e32 v132, v2
	v_mov_b32_e32 v133, v2
	v_mov_b32_e32 v134, v2
	v_mov_b32_e32 v135, v2
	v_mov_b32_e32 v136, v2
	v_mov_b32_e32 v137, v2
	v_mov_b32_e32 v146, v2
	v_mov_b32_e32 v147, v2
	v_mov_b32_e32 v148, v2
	v_mov_b32_e32 v149, v2
	v_mov_b32_e32 v150, v2
	v_mov_b32_e32 v151, v2
	v_mov_b32_e32 v152, v2
	v_mov_b32_e32 v153, v2
	v_mov_b32_e32 v162, v2
	v_mov_b32_e32 v163, v2
	v_mov_b32_e32 v164, v2
	v_mov_b32_e32 v165, v2
	v_mov_b32_e32 v166, v2
	v_mov_b32_e32 v167, v2
	v_mov_b32_e32 v168, v2
	v_mov_b32_e32 v169, v2
	v_mov_b32_e32 v122, v2
	v_mov_b32_e32 v123, v2
	v_mov_b32_e32 v124, v2
	v_mov_b32_e32 v125, v2
	v_mov_b32_e32 v126, v2
	v_mov_b32_e32 v127, v2
	v_mov_b32_e32 v128, v2
	v_mov_b32_e32 v129, v2
	v_mov_b32_e32 v138, v2
	v_mov_b32_e32 v139, v2
	v_mov_b32_e32 v140, v2
	v_mov_b32_e32 v141, v2
	v_mov_b32_e32 v142, v2
	v_mov_b32_e32 v143, v2
	v_mov_b32_e32 v144, v2
	v_mov_b32_e32 v145, v2
	v_mov_b32_e32 v154, v2
	v_mov_b32_e32 v155, v2
	v_mov_b32_e32 v156, v2
	v_mov_b32_e32 v157, v2
	v_mov_b32_e32 v158, v2
	v_mov_b32_e32 v159, v2
	v_mov_b32_e32 v160, v2
	v_mov_b32_e32 v161, v2
	v_mov_b32_e32 v170, v2
	v_mov_b32_e32 v171, v2
	v_mov_b32_e32 v172, v2
	v_mov_b32_e32 v173, v2
	v_mov_b32_e32 v174, v2
	v_mov_b32_e32 v175, v2
	v_mov_b32_e32 v176, v2
	v_mov_b32_e32 v177, v2
	.p2alignl 6, 3212836864

; template <class Epi, bool ALIGN_EPI = true>
; __device__ __forceinline__ void gemm_phase(LAS unsigned char* lds, const Gemm g, const Order& S, const Epi& E) {
;     ...
;         const bool has_next = S.next(ui + 1, nxt);
;         const char* nA = has_next ? (const char*)g.A + (size_t)nxt.pm * tstepA + (size_t)(nxt.k0 >> 6) * kstepA : cA; const char* nB = has_next ? (const char*)g.Bt + (size_t)nxt.pn * tstepB + (size_t)(nxt.k0 >> 6) * kstepB : cB;
;         const int nt = cur.nt;
;         for (int t = 0; t < nt; t += 2) {
;             const bool last = (t == nt - 2);
;             const char* a1 = cA + (size_t)(t + 1) * kstepA;
;             const char* a2 = last ? nA : cA + (size_t)(t + 2) * kstepA; const char* b2 = last ? nB : cB + (size_t)(t + 2) * kstepB;
;             const char* a3 = a2 + kstepA; const char* b3 = b2 + kstepB;
;     ...
; #pragma unroll
;         for (int a = 0; a < 2; ++a)
; #pragma unroll
;             for (int b = 0; b < 2; ++b)
; #pragma unroll
;                 for (int m = 0; m < 4; ++m)
; #pragma unroll
;                     for (int n = 0; n < 2; ++n) acc[a][b][m][n] = (f32x4){0.f, 0.f, 0.f, 0.f};
;         cur = nxt; cA = nA; cB = nB; ++ui;
.LBB0_373:
	s_ashr_i32 s45, s44, 31
	s_lshl_b64 s[48:49], s[44:45], 19
	v_readlane_b32 s28, v253, 18
	v_readlane_b32 s29, v253, 19
	s_add_u32 s41, s28, s48
	s_addc_u32 s45, s29, s49
	s_add_u32 s48, s41, s50
	s_addc_u32 s49, s45, s51
	s_and_b64 s[60:61], s[46:47], exec
	s_cselect_b32 s45, s49, s57
	s_cselect_b32 s53, s48, s56
	s_ashr_i32 s41, s40, 31
	s_lshl_b64 s[60:61], s[40:41], 19
	s_add_u32 s41, s67, s60
	s_addc_u32 s55, s68, s61
	s_add_u32 s50, s41, s50
	s_addc_u32 s51, s55, s51
	s_and_b64 s[60:61], s[46:47], exec
	s_cselect_b32 s41, s51, s59
	s_cselect_b32 s55, s50, s58
	s_add_i32 s86, s84, -2
	s_add_u32 s56, s56, 0xc000
	s_addc_u32 s57, s57, 0
	s_add_u32 s87, s58, 0x10000
	v_mov_b32_e32 v2, 0
	s_mov_b32 s43, s63
	s_addc_u32 s88, s59, 0
	s_mov_b32 s58, 0
	v_mov_b32_e32 v3, v2
	v_mov_b32_e32 v4, v2
	v_mov_b32_e32 v5, v2
	v_mov_b32_e32 v6, v2
	v_mov_b32_e32 v7, v2
	v_mov_b32_e32 v8, v2
	v_mov_b32_e32 v9, v2
	v_mov_b32_e32 v18, v2
	v_mov_b32_e32 v19, v2
	v_mov_b32_e32 v20, v2
	v_mov_b32_e32 v21, v2
	v_mov_b32_e32 v22, v2
	v_mov_b32_e32 v23, v2
	v_mov_b32_e32 v24, v2
	v_mov_b32_e32 v25, v2
	v_mov_b32_e32 v34, v2
	v_mov_b32_e32 v35, v2
	v_mov_b32_e32 v36, v2
	v_mov_b32_e32 v37, v2
	v_mov_b32_e32 v38, v2
	v_mov_b32_e32 v39, v2
	v_mov_b32_e32 v40, v2
	v_mov_b32_e32 v41, v2
	v_mov_b32_e32 v50, v2
	v_mov_b32_e32 v51, v2
	v_mov_b32_e32 v52, v2
	v_mov_b32_e32 v53, v2
	v_mov_b32_e32 v54, v2
	v_mov_b32_e32 v55, v2
	v_mov_b32_e32 v56, v2
	v_mov_b32_e32 v57, v2
	v_mov_b32_e32 v10, v2
	v_mov_b32_e32 v11, v2
	v_mov_b32_e32 v12, v2
	v_mov_b32_e32 v13, v2
	v_mov_b32_e32 v14, v2
	v_mov_b32_e32 v15, v2
	v_mov_b32_e32 v16, v2
	v_mov_b32_e32 v17, v2
	v_mov_b32_e32 v26, v2
	v_mov_b32_e32 v27, v2
	v_mov_b32_e32 v28, v2
	v_mov_b32_e32 v29, v2
	v_mov_b32_e32 v30, v2
	v_mov_b32_e32 v31, v2
	v_mov_b32_e32 v32, v2
	v_mov_b32_e32 v33, v2
	v_mov_b32_e32 v42, v2
	v_mov_b32_e32 v43, v2
	v_mov_b32_e32 v44, v2
	v_mov_b32_e32 v45, v2
	v_mov_b32_e32 v46, v2
	v_mov_b32_e32 v47, v2
	v_mov_b32_e32 v48, v2
	v_mov_b32_e32 v49, v2
	v_mov_b32_e32 v58, v2
	v_mov_b32_e32 v59, v2
	v_mov_b32_e32 v60, v2
	v_mov_b32_e32 v61, v2
	v_mov_b32_e32 v70, v2
	v_mov_b32_e32 v71, v2
	v_mov_b32_e32 v72, v2
	v_mov_b32_e32 v73, v2
	v_mov_b32_e32 v114, v2
	v_mov_b32_e32 v115, v2
	v_mov_b32_e32 v116, v2
	v_mov_b32_e32 v117, v2
	v_mov_b32_e32 v118, v2
	v_mov_b32_e32 v119, v2
	v_mov_b32_e32 v120, v2
	v_mov_b32_e32 v121, v2
	v_mov_b32_e32 v130, v2
	v_mov_b32_e32 v131, v2
	v_mov_b32_e32 v132, v2
	v_mov_b32_e32 v133, v2
	v_mov_b32_e32 v134, v2
	v_mov_b32_e32 v135, v2
	v_mov_b32_e32 v136, v2
	v_mov_b32_e32 v137, v2
	v_mov_b32_e32 v146, v2
	v_mov_b32_e32 v147, v2
	v_mov_b32_e32 v148, v2
	v_mov_b32_e32 v149, v2
	v_mov_b32_e32 v150, v2
	v_mov_b32_e32 v151, v2
	v_mov_b32_e32 v152, v2
	v_mov_b32_e32 v153, v2
	v_mov_b32_e32 v162, v2
	v_mov_b32_e32 v163, v2
	v_mov_b32_e32 v164, v2
	v_mov_b32_e32 v165, v2
	v_mov_b32_e32 v166, v2
	v_mov_b32_e32 v167, v2
	v_mov_b32_e32 v168, v2
	v_mov_b32_e32 v169, v2
	v_mov_b32_e32 v122, v2
	v_mov_b32_e32 v123, v2
	v_mov_b32_e32 v124, v2
	v_mov_b32_e32 v125, v2
	v_mov_b32_e32 v126, v2
	v_mov_b32_e32 v127, v2
	v_mov_b32_e32 v128, v2
	v_mov_b32_e32 v129, v2
	v_mov_b32_e32 v138, v2
	v_mov_b32_e32 v139, v2
	v_mov_b32_e32 v140, v2
	v_mov_b32_e32 v141, v2
	v_mov_b32_e32 v142, v2
	v_mov_b32_e32 v143, v2
	v_mov_b32_e32 v144, v2
	v_mov_b32_e32 v145, v2
	v_mov_b32_e32 v154, v2
	v_mov_b32_e32 v155, v2
	v_mov_b32_e32 v156, v2
	v_mov_b32_e32 v157, v2
	v_mov_b32_e32 v158, v2
	v_mov_b32_e32 v159, v2
	v_mov_b32_e32 v160, v2
	v_mov_b32_e32 v161, v2
	v_mov_b32_e32 v170, v2
	v_mov_b32_e32 v171, v2
	v_mov_b32_e32 v172, v2
	v_mov_b32_e32 v173, v2
	v_mov_b32_e32 v174, v2
	v_mov_b32_e32 v175, v2
	v_mov_b32_e32 v176, v2
	v_mov_b32_e32 v177, v2
	.p2alignl 6, 3212836864

; template <class Epi, bool ALIGN_EPI = true>
; __device__ __forceinline__ void gemm_phase(LAS unsigned char* lds, const Gemm g, const Order& S, const Epi& E) {
;     ...
;         const bool has_next = S.next(ui + 1, nxt);
;         const char* nA = has_next ? (const char*)g.A + (size_t)nxt.pm * tstepA + (size_t)(nxt.k0 >> 6) * kstepA : cA; const char* nB = has_next ? (const char*)g.Bt + (size_t)nxt.pn * tstepB + (size_t)(nxt.k0 >> 6) * kstepB : cB;
;         const int nt = cur.nt;
;         for (int t = 0; t < nt; t += 2) {
;             const bool last = (t == nt - 2);
;             const char* a1 = cA + (size_t)(t + 1) * kstepA;
;             const char* a2 = last ? nA : cA + (size_t)(t + 2) * kstepA; const char* b2 = last ? nB : cB + (size_t)(t + 2) * kstepB;
;             const char* a3 = a2 + kstepA; const char* b3 = b2 + kstepB;
.LBB0_892:
	s_xor_b64 s[48:49], s[56:57], -1
	s_add_u32 s80, s52, 0x10000
	s_addc_u32 s81, s53, 0
	s_ashr_i32 s47, s46, 31
	s_lshl_b64 s[34:35], s[46:47], 19
	s_add_u32 s54, s92, s34
	s_addc_u32 s55, s93, s35
	s_and_b64 s[34:35], s[56:57], exec
	s_cselect_b32 s34, s55, s41
	s_cselect_b32 s35, s54, s40
	s_ashr_i32 s45, s44, 31
	s_lshl_b64 s[50:51], s[44:45], 19
	s_add_u32 s50, s10, s50
	s_addc_u32 s51, s90, s51
	s_and_b64 s[58:59], s[56:57], exec
	s_cselect_b32 s45, s51, s53
	s_cselect_b32 s47, s50, s52
	s_add_u32 s52, s40, 0xc000
	s_addc_u32 s53, s41, 0
	v_lshl_add_u64 v[130:131], s[52:53], 0, v[206:207]
	v_lshl_add_u64 v[132:133], s[52:53], 0, v[158:159]
	s_mov_b32 s82, -2
	s_mov_b64 s[52:53], 0
	.p2alignl 6, 3212836864
